# v18 with the designated early L2 write-back after P1 delayed by ~15.5us (4 x s_sleep 127)
# baseline (speedup 1.0000x reference)
.LBB0_617:
	s_waitcnt vmcnt(0)
	s_waitcnt vmcnt(0)
	s_barrier
	s_mov_b64 s[0:1], exec
	v_readlane_b32 s8, v245, 16
	v_readlane_b32 s9, v245, 17
	v_readlane_b32 s22, v244, 19
	s_and_b64 s[8:9], s[0:1], s[8:9]
	v_readlane_b32 s23, v244, 20
	s_mov_b64 exec, s[8:9]
	s_cbranch_execz .LBB0_669
	s_cmp_lt_u32 s2, 0xf8
	s_cbranch_scc1 .Lwb1_skip0
	s_sleep 127
	s_sleep 127
	s_sleep 127
	s_sleep 127
	buffer_wbl2 sc1
	s_waitcnt vmcnt(0)
